# in-projection tile order: XCD super-tiles of 4 M-tiles x 16 N-pairs (each activation row panel read once per XCD) instead of 8 x 8
# speedup vs baseline: 1.0240x; 1.0073x over previous
.LBB0_232:
	s_ashr_i32 s0, s3, 4
	s_and_b32 s0, s0, -4
	s_add_i32 s0, s0, s43
	s_and_b32 s1, s3, 3
	s_or_b32 s76, s0, s1
	s_lshr_b32 s0, s3, 1
	s_and_b32 s74, s0, 30
	s_mov_b32 s52, 1
	s_cmp_lt_i32 s52, 2
	s_mov_b64 s[0:1], -1
	s_cbranch_scc1 .LBB0_222
